# v45: v44 + attention step: the 1 KiB lambda parameter block staged into LDS by LDS-DMA at step entry (hidden behind the pool phase); the four serial rounds of global loads became LDS reads
# speedup vs baseline: 1.0100x; 1.0025x over previous
.LBB0_155:
	s_and_b64 vcc, exec, s[0:1]
	s_cbranch_vccz .LBB0_266
	v_readlane_b32 s8, v246, 37
	v_readlane_b32 s12, v246, 41
	v_readlane_b32 s13, v246, 42
	s_mov_b64 s[0:1], s[12:13]
	s_add_u32 s40, s0, 0xe000000
	s_addc_u32 s41, s1, 0
	v_and_b32_e32 v1, 63, v195
	v_lshlrev_b32_e32 v1, 4, v1
	s_lshl_b32 s2, s65, 9
	s_add_u32 s2, s94, s2
	s_addc_u32 s3, s95, 0
	s_mov_b32 m0, 0x1e000
	s_nop 0
	global_load_lds_dwordx4 v1, s[2:3]
	v_mov_b32_e32 v0, v195
	s_add_u32 s42, s0, 0xa000000
	s_addc_u32 s43, s1, 0
	v_add_u32_e32 v184, s69, v0
	v_cmp_gt_i32_e32 vcc, s35, v184
	v_readlane_b32 s9, v246, 38
	v_readlane_b32 s10, v246, 39
	v_readlane_b32 s11, v246, 40
	v_readlane_b32 s14, v246, 43
	v_readlane_b32 s15, v246, 44
	s_and_saveexec_b64 s[2:3], vcc
	s_cbranch_execz .LBB0_225
	s_waitcnt lgkmcnt(0)
	v_and_b32_e32 v1, 63, v0
	v_lshlrev_b32_e32 v192, 4, v1
	v_cmp_lt_u32_e64 s[36:37], 15, v1
	v_bfe_u32 v185, v0, 4, 2
	v_lshl_add_u64 v[104:105], s[40:41], 0, v[192:193]
	v_lshl_add_u64 v[106:107], s[42:43], 0, v[192:193]
	s_mov_b64 s[6:7], 0
	s_branch .LBB0_160

.LBB0_225:
	s_or_b64 exec, exec, s[2:3]
	s_waitcnt vmcnt(16)
	s_lshl_b32 s2, s65, 9
	s_add_u32 s5, s94, s2
	s_addc_u32 s8, s95, 0
	s_mov_b64 s[2:3], 0
	s_waitcnt lgkmcnt(0)
	v_mov_b32_e32 v1, 0
	v_mov_b32_e32 v0, 0
.LBB0_226:
	s_add_u32 s6, s5, s2
	s_addc_u32 s7, s8, s3
	v_mov_b32_e32 v66, s2
	v_add_u32_e32 v66, 0x1e000, v66
	ds_read_b128 v[2:5], v66 offset:48
	ds_read_b128 v[6:9], v66 offset:32
	ds_read_b128 v[10:13], v66 offset:16
	ds_read_b128 v[14:17], v66
	ds_read_b128 v[18:21], v66 offset:304
	ds_read_b128 v[22:25], v66 offset:288
	ds_read_b128 v[26:29], v66 offset:272
	ds_read_b128 v[30:33], v66 offset:256
	ds_read_b128 v[34:37], v66 offset:560
	ds_read_b128 v[38:41], v66 offset:544
	ds_read_b128 v[42:45], v66 offset:528
	ds_read_b128 v[46:49], v66 offset:512
	ds_read_b128 v[50:53], v66 offset:816
	ds_read_b128 v[54:57], v66 offset:800
	ds_read_b128 v[58:61], v66 offset:784
	ds_read_b128 v[62:65], v66 offset:768
	s_add_u32 s2, s2, 64
	s_addc_u32 s3, s3, 0
	s_cmpk_eq_i32 s2, 0x100
	s_waitcnt lgkmcnt(0)
	v_mov_b32_e32 v66, v14
	v_mov_b32_e32 v14, v16
	v_mov_b32_e32 v16, v26
	v_mov_b32_e32 v68, v30
	v_mov_b32_e32 v30, v32
	v_mov_b32_e32 v67, v46
	v_mov_b32_e32 v46, v15
	v_mov_b32_e32 v15, v48
	v_mov_b32_e32 v48, v17
	v_mov_b32_e32 v69, v62
	v_pk_fma_f32 v[0:1], v[66:67], v[68:69], v[0:1]
	v_mov_b32_e32 v62, v31
	v_pk_fma_f32 v[0:1], v[46:47], v[62:63], v[0:1]
	v_mov_b32_e32 v31, v64
	v_pk_fma_f32 v[0:1], v[14:15], v[30:31], v[0:1]
	v_mov_b32_e32 v64, v33
	v_pk_fma_f32 v[0:1], v[48:49], v[64:65], v[0:1]
	v_mov_b32_e32 v14, v10
	v_mov_b32_e32 v15, v42
	v_mov_b32_e32 v17, v58
	v_pk_fma_f32 v[0:1], v[14:15], v[16:17], v[0:1]
	v_mov_b32_e32 v42, v11
	v_mov_b32_e32 v58, v27
	v_pk_fma_f32 v[0:1], v[42:43], v[58:59], v[0:1]
	v_mov_b32_e32 v10, v12
	v_mov_b32_e32 v11, v44
	v_mov_b32_e32 v14, v28
	v_mov_b32_e32 v15, v60
	v_pk_fma_f32 v[0:1], v[10:11], v[14:15], v[0:1]
	v_mov_b32_e32 v44, v13
	v_mov_b32_e32 v60, v29
	v_pk_fma_f32 v[0:1], v[44:45], v[60:61], v[0:1]
	v_mov_b32_e32 v10, v6
	v_mov_b32_e32 v11, v38
	v_mov_b32_e32 v12, v22
	v_mov_b32_e32 v13, v54
	v_pk_fma_f32 v[0:1], v[10:11], v[12:13], v[0:1]
	v_mov_b32_e32 v38, v7
	v_mov_b32_e32 v54, v23
	v_pk_fma_f32 v[0:1], v[38:39], v[54:55], v[0:1]
	v_mov_b32_e32 v6, v8
	v_mov_b32_e32 v7, v40
	v_mov_b32_e32 v10, v24
	v_mov_b32_e32 v11, v56
	v_pk_fma_f32 v[0:1], v[6:7], v[10:11], v[0:1]
	v_mov_b32_e32 v40, v9
	v_mov_b32_e32 v56, v25
	v_pk_fma_f32 v[0:1], v[40:41], v[56:57], v[0:1]
	v_mov_b32_e32 v6, v2
	v_mov_b32_e32 v7, v34
	v_mov_b32_e32 v8, v18
	v_mov_b32_e32 v9, v50
	v_pk_fma_f32 v[0:1], v[6:7], v[8:9], v[0:1]
	v_mov_b32_e32 v34, v3
	v_mov_b32_e32 v50, v19
	v_pk_fma_f32 v[0:1], v[34:35], v[50:51], v[0:1]
	v_mov_b32_e32 v2, v4
	v_mov_b32_e32 v3, v36
	v_mov_b32_e32 v6, v20
	v_mov_b32_e32 v7, v52
	v_pk_fma_f32 v[0:1], v[2:3], v[6:7], v[0:1]
	v_mov_b32_e32 v36, v5
	v_mov_b32_e32 v52, v21
	v_pk_fma_f32 v[0:1], v[36:37], v[52:53], v[0:1]
	s_cbranch_scc0 .LBB0_226
	v_readlane_b32 s2, v247, 29
	v_readlane_b32 s3, v247, 30
	s_andn2_b64 vcc, exec, s[2:3]
	s_cbranch_vccnz .LBB0_266
	v_cvt_f32_ubyte0_e32 v2, s65
	v_mul_f32_e32 v2, 0xbe99999a, v2
	v_mul_f32_e32 v3, 0x3fb8aa3b, v2
	s_mov_b32 s2, 0x3fb8aa3b
	v_fma_f32 v4, v2, s2, -v3
	v_rndne_f32_e32 v5, v3
	v_fmac_f32_e32 v4, 0x32a5705f, v2
	v_sub_f32_e32 v3, v3, v5
	v_add_f32_e32 v3, v3, v4
	v_exp_f32_e32 v3, v3
	v_cvt_i32_f32_e32 v4, v5
	s_mov_b32 s3, 0xc2ce8ed0
	v_cmp_ngt_f32_e32 vcc, s3, v2
	s_mov_b32 s5, 0x42b17218
	v_ldexp_f32 v3, v3, v4
	v_cndmask_b32_e32 v3, 0, v3, vcc
	v_cmp_nlt_f32_e32 vcc, s5, v2
	s_nop 1
	v_cndmask_b32_e32 v2, v212, v3, vcc
	v_mul_f32_e32 v3, 0x3fb8aa3b, v0
	v_rndne_f32_e32 v4, v3
	v_sub_f32_e32 v5, v3, v4
	v_fma_f32 v3, v0, s2, -v3
	v_fmac_f32_e32 v3, 0x32a5705f, v0
	v_add_f32_e32 v3, v5, v3
	v_exp_f32_e32 v3, v3
	v_cvt_i32_f32_e32 v4, v4
	v_cmp_ngt_f32_e32 vcc, s3, v0
	v_fmamk_f32 v2, v2, 0xbf19999a, v199
	v_sub_f32_e32 v191, 1.0, v2
	v_ldexp_f32 v3, v3, v4
	v_cndmask_b32_e32 v3, 0, v3, vcc
	v_cmp_nlt_f32_e32 vcc, s5, v0
	s_nop 1
	v_cndmask_b32_e32 v0, v212, v3, vcc
	v_mul_f32_e32 v3, 0x3fb8aa3b, v1
	v_rndne_f32_e32 v4, v3
	v_sub_f32_e32 v5, v3, v4
	v_fma_f32 v3, v1, s2, -v3
	v_fmac_f32_e32 v3, 0x32a5705f, v1
	v_add_f32_e32 v3, v5, v3
	v_exp_f32_e32 v3, v3
	v_cvt_i32_f32_e32 v4, v4
	s_lshl_b32 s2, s65, 8
	s_add_u32 s38, s96, s2
	v_cmp_ngt_f32_e32 vcc, s3, v1
	v_ldexp_f32 v3, v3, v4
	s_addc_u32 s39, s97, 0
	v_cndmask_b32_e32 v3, 0, v3, vcc
	v_cmp_nlt_f32_e32 vcc, s5, v1
	s_add_u32 s80, s0, 0x16000000
	s_addc_u32 s2, s1, 0
	v_cndmask_b32_e32 v1, v212, v3, vcc
	v_sub_f32_e32 v0, v0, v1
	v_writelane_b32 v245, s2, 34
	s_add_u32 s24, s0, 0xe0c0400
	v_readlane_b32 s2, v247, 0
	v_add_f32_e32 v190, v2, v0
	s_addc_u32 s26, s1, 0
	v_readlane_b32 s25, v245, 9
	s_mov_b32 s44, s2
	s_branch .LBB0_230
